# speedup vs baseline: 1.0010x; 1.0010x over previous
; DI unsigned pack2(float a, float b) { v2f f = {a, b}; return __builtin_bit_cast(unsigned, __builtin_convertvector(f, v2bf)); }
; DI float bflo(unsigned v) { return __uint_as_float(v << 16); }
; DI float bfhi(unsigned v) { return __uint_as_float(v & 0xffff0000u); }
; DI int ltid() { int x = threadIdx.x; asm volatile("" : "+v"(x)); return x; }
; DI int lbid() { int x = blockIdx.x; asm volatile("" : "+s"(x)); return x; }
; DI void cmp2_phase(const Params& p) {
;   const int tid = ltid(), nn = tid & 63, rr = tid >> 6;
;   for (int task = lbid(); task < 2048; task += gridDim.x) {
;     const int c = task >> 10, m = (task & 1023) * 4 + rr;
;     const u16* hrow = p.h1 + ((long)c * 4096 + m) * 256;
;     const float* w2 = p.a_w2_k; if (c) w2 = p.a_w2_v;
;     float s = 0.f;
;     for (int k = 0; k < 256; k += 2) {
;       const unsigned hv = *(const unsigned*)(hrow + k);
;       s += bflo(hv) * w2[k * 64 + nn] + bfhi(hv) * w2[(k + 1) * 64 + nn];
;     }
;     if ((m & 511) == 511) s = 0.f;
;     u16* dstp = p.kcmp; if (c) dstp = p.vcmp; dstp += (long)m * 64 + nn;
;     *dstp = (u16)(pack2(s, 0.f) & 0xffffu);
;     if (c == 0) {
;       float ss = s * s;
; #pragma unroll
;       for (int o = 32; o > 0; o >>= 1) ss += __shfl_xor(ss, o);
;       if (nn == 0) atomicMax(p.kmax2 + 480 + (m >> 9), __float_as_uint(ss));
;     }
;   }
; }
.Lcmp2_have_w:
	v_add_u32_e32 v96, 0xfffff100, v2
	global_load_dwordx4 v[52:55], v[8:9], off offset:-28
	global_load_dwordx4 v[56:59], v[8:9], off offset:-12
.LBB0_740:
	s_waitcnt vmcnt(0)
	v_mov_b32_e32 v20, v52
	v_mov_b32_e32 v21, v53
	v_mov_b32_e32 v22, v54
	v_mov_b32_e32 v23, v55
	v_mov_b32_e32 v24, v56
	v_mov_b32_e32 v25, v57
	v_mov_b32_e32 v26, v58
	v_mov_b32_e32 v27, v59
	global_load_dwordx4 v[52:55], v[8:9], off offset:4
	global_load_dwordx4 v[56:59], v[8:9], off offset:20
	ds_read_b32 v28, v96
	ds_read_b32 v29, v96 offset:256
	ds_read_b32 v30, v96 offset:512
	ds_read_b32 v31, v96 offset:768
	ds_read_b32 v32, v96 offset:1024
	ds_read_b32 v33, v96 offset:1280
	ds_read_b32 v34, v96 offset:1536
	ds_read_b32 v35, v96 offset:1792
	ds_read_b32 v36, v96 offset:2048
	ds_read_b32 v37, v96 offset:2304
	ds_read_b32 v38, v96 offset:2560
	ds_read_b32 v39, v96 offset:2816
	ds_read_b32 v40, v96 offset:3072
	ds_read_b32 v41, v96 offset:3328
	ds_read_b32 v42, v96 offset:3584
	ds_read_b32 v43, v96 offset:3840
	s_add_i32 s6, s6, 16
	v_add_u32_e32 v96, 0x1000, v96
	v_lshl_add_u64 v[8:9], v[8:9], 0, 32
	s_cmpk_gt_u32 s6, 0xfd
	v_lshlrev_b32_e32 v44, 16, v20
	v_and_b32_e32 v45, 0xffff0000, v20
	v_lshlrev_b32_e32 v20, 16, v21
	v_and_b32_e32 v21, 0xffff0000, v21
	s_waitcnt lgkmcnt(14)
	v_pk_mul_f32 v[28:29], v[28:29], v[44:45]
	v_lshlrev_b32_e32 v46, 16, v22
	v_and_b32_e32 v47, 0xffff0000, v22
	s_waitcnt lgkmcnt(12)
	v_pk_mul_f32 v[20:21], v[30:31], v[20:21]
	v_add_f32_e32 v28, v28, v29
	v_lshlrev_b32_e32 v22, 16, v23
	v_and_b32_e32 v23, 0xffff0000, v23
	s_waitcnt lgkmcnt(10)
	v_pk_mul_f32 v[30:31], v[32:33], v[46:47]
	v_add_f32_e32 v20, v20, v21
	v_add_f32_e32 v19, v19, v28
	v_lshlrev_b32_e32 v48, 16, v24
	v_and_b32_e32 v49, 0xffff0000, v24
	s_waitcnt lgkmcnt(8)
	v_pk_mul_f32 v[22:23], v[34:35], v[22:23]
	v_add_f32_e32 v21, v30, v31
	v_add_f32_e32 v19, v19, v20
	v_lshlrev_b32_e32 v24, 16, v25
	v_and_b32_e32 v25, 0xffff0000, v25
	s_waitcnt lgkmcnt(6)
	v_pk_mul_f32 v[32:33], v[36:37], v[48:49]
	v_add_f32_e32 v22, v22, v23
	v_add_f32_e32 v19, v19, v21
	v_lshlrev_b32_e32 v50, 16, v26
	v_and_b32_e32 v51, 0xffff0000, v26
	s_waitcnt lgkmcnt(4)
	v_pk_mul_f32 v[24:25], v[38:39], v[24:25]
	v_add_f32_e32 v23, v32, v33
	v_add_f32_e32 v19, v19, v22
	v_lshlrev_b32_e32 v26, 16, v27
	v_and_b32_e32 v27, 0xffff0000, v27
	s_waitcnt lgkmcnt(2)
	v_pk_mul_f32 v[34:35], v[40:41], v[50:51]
	v_add_f32_e32 v24, v24, v25
	v_add_f32_e32 v19, v19, v23
	s_waitcnt lgkmcnt(0)
	v_pk_mul_f32 v[26:27], v[42:43], v[26:27]
	v_add_f32_e32 v25, v34, v35
	v_add_f32_e32 v19, v19, v24
	v_add_f32_e32 v26, v26, v27
	v_add_f32_e32 v19, v19, v25
	v_add_f32_e32 v19, v19, v26
	s_cbranch_scc0 .LBB0_740
	s_lshl_b32 s6, s12, 2
	s_and_b32 s6, s6, 0xffc
	s_and_b64 vcc, s[0:1], exec
	s_cselect_b32 s0, s17, 0x158
	s_add_u32 s0, s56, s0
	s_addc_u32 s1, s57, 0
	s_load_dwordx2 s[0:1], s[0:1], 0x0
	v_add_u32_e32 v8, s6, v0
	v_ashrrev_i32_e32 v9, 31, v8
	v_and_b32_e32 v10, 0x1ff, v8
	v_cmp_ne_u32_e64 s[6:7], s16, v10
	v_lshlrev_b64 v[20:21], 7, v[8:9]
	s_waitcnt lgkmcnt(0)
	v_lshl_add_u64 v[20:21], s[0:1], 0, v[20:21]
	v_cndmask_b32_e64 v10, 0, v19, s[6:7]
	v_lshl_add_u64 v[20:21], v[20:21], 0, v[6:7]
	v_cvt_pk_bf16_f32 v9, v10, s0
	global_store_short v[20:21], v9, off
	s_cbranch_vccz .LBB0_738
	v_cmp_lt_i32_e32 vcc, v13, v12
	v_mul_f32_e32 v9, v10, v10
	s_nop 0
	v_cndmask_b32_e32 v11, v1, v13, vcc
	v_lshlrev_b32_e32 v11, 2, v11
	ds_bpermute_b32 v9, v11, v9
	v_cmp_lt_i32_e32 vcc, v14, v12
	s_waitcnt lgkmcnt(0)
	v_fmac_f32_e32 v9, v10, v10
	v_cndmask_b32_e32 v11, v1, v14, vcc
	v_lshlrev_b32_e32 v10, 2, v11
	ds_bpermute_b32 v10, v10, v9
	v_cmp_lt_i32_e32 vcc, v15, v12
	s_waitcnt lgkmcnt(0)
	v_add_f32_e32 v9, v9, v10
	v_cndmask_b32_e32 v11, v1, v15, vcc
	v_lshlrev_b32_e32 v11, 2, v11
	ds_bpermute_b32 v10, v11, v9
	v_cmp_lt_i32_e32 vcc, v16, v12
	s_waitcnt lgkmcnt(0)
	v_add_f32_e32 v9, v9, v10
	v_cndmask_b32_e32 v11, v1, v16, vcc
	v_lshlrev_b32_e32 v11, 2, v11
	ds_bpermute_b32 v10, v11, v9
	v_cmp_lt_i32_e32 vcc, v17, v12
	s_waitcnt lgkmcnt(0)
	v_add_f32_e32 v9, v9, v10
	v_cndmask_b32_e32 v11, v1, v17, vcc
	v_lshlrev_b32_e32 v11, 2, v11
	ds_bpermute_b32 v10, v11, v9
	v_cmp_lt_i32_e32 vcc, v18, v12
	s_waitcnt lgkmcnt(0)
	v_add_f32_e32 v9, v9, v10
	v_cndmask_b32_e32 v11, v1, v18, vcc
	v_lshlrev_b32_e32 v10, 2, v11
	ds_bpermute_b32 v10, v10, v9
	s_and_saveexec_b64 s[0:1], s[4:5]
	s_cbranch_execz .LBB0_737
	v_ashrrev_i32_e32 v20, 9, v8
	v_ashrrev_i32_e32 v21, 31, v20
	s_waitcnt lgkmcnt(0)
	v_add_f32_e32 v10, v9, v10
	v_lshl_add_u64 v[8:9], v[20:21], 2, s[2:3]
	global_load_dword v20, v[8:9], off offset:1920 sc1
	s_waitcnt vmcnt(0)
	v_cmp_gt_u32_e32 vcc, v10, v20
	s_and_b64 exec, exec, vcc
	s_cbranch_execz .LBB0_737
	global_atomic_umax v[8:9], v10, off offset:1920
	s_branch .LBB0_737
